# prep1: ctx-token new_na_k/new_na_v output conversion loop rewritten with all 16 loads in flight and counted waits (was 16 serialized load-wait-store round trips per thread)
# speedup vs baseline: 1.0091x; 1.0004x over previous
.LBB0_596:
	s_or_b64 exec, exec, s[4:5]
	v_and_b32_e32 v246, 0xff, v11
	v_ashrrev_i32_e32 v247, 8, v11
	v_readlane_b32 s0, v254, 62
	v_readlane_b32 s1, v254, 63
	v_mul_u32_u24_e32 v102, 0x1800, v247
	v_lshl_add_u32 v102, v246, 4, v102
	v_mov_b32_e32 v103, 0
	s_nop 1
	v_lshl_add_u64 v[102:103], s[0:1], 0, v[102:103]
	s_mov_b64 s[4:5], 0x300000
	global_load_dwordx4 v[182:185], v[102:103], off offset:2048
	v_lshl_add_u64 v[102:103], v[102:103], 0, s[4:5]
	global_load_dwordx4 v[186:189], v[102:103], off offset:2048
	v_lshl_add_u64 v[102:103], v[102:103], 0, s[4:5]
	global_load_dwordx4 v[190:193], v[102:103], off offset:2048
	v_lshl_add_u64 v[102:103], v[102:103], 0, s[4:5]
	global_load_dwordx4 v[194:197], v[102:103], off offset:2048
	v_lshl_add_u64 v[102:103], v[102:103], 0, s[4:5]
	global_load_dwordx4 v[198:201], v[102:103], off offset:2048
	v_lshl_add_u64 v[102:103], v[102:103], 0, s[4:5]
	global_load_dwordx4 v[202:205], v[102:103], off offset:2048
	v_lshl_add_u64 v[102:103], v[102:103], 0, s[4:5]
	global_load_dwordx4 v[206:209], v[102:103], off offset:2048
	v_lshl_add_u64 v[102:103], v[102:103], 0, s[4:5]
	global_load_dwordx4 v[210:213], v[102:103], off offset:2048
	v_lshl_add_u64 v[102:103], v[102:103], 0, s[4:5]
	global_load_dwordx4 v[214:217], v[102:103], off offset:2048
	v_lshl_add_u64 v[102:103], v[102:103], 0, s[4:5]
	global_load_dwordx4 v[218:221], v[102:103], off offset:2048
	v_lshl_add_u64 v[102:103], v[102:103], 0, s[4:5]
	global_load_dwordx4 v[222:225], v[102:103], off offset:2048
	v_lshl_add_u64 v[102:103], v[102:103], 0, s[4:5]
	global_load_dwordx4 v[226:229], v[102:103], off offset:2048
	v_lshl_add_u64 v[102:103], v[102:103], 0, s[4:5]
	global_load_dwordx4 v[230:233], v[102:103], off offset:2048
	v_lshl_add_u64 v[102:103], v[102:103], 0, s[4:5]
	global_load_dwordx4 v[234:237], v[102:103], off offset:2048
	v_lshl_add_u64 v[102:103], v[102:103], 0, s[4:5]
	global_load_dwordx4 v[238:241], v[102:103], off offset:2048
	v_lshl_add_u64 v[102:103], v[102:103], 0, s[4:5]
	global_load_dwordx4 v[242:245], v[102:103], off offset:2048
	v_readlane_b32 s6, v255, 8
	v_readlane_b32 s7, v255, 9
	v_readlane_b32 s8, v252, 58
	v_readlane_b32 s9, v252, 59
	s_add_u32 s8, s8, 0xcfff000
	s_addc_u32 s9, s9, 0
	v_mov_b32_e32 v104, s6
	v_mov_b32_e32 v105, s7
	v_mov_b32_e32 v106, s8
	v_mov_b32_e32 v107, s9
	v_cmp_lt_u32_e32 vcc, 0x7f, v246
	v_cndmask_b32_e32 v100, v104, v106, vcc
	v_cndmask_b32_e32 v101, v105, v107, vcc
	v_lshlrev_b32_e32 v104, 12, v247
	v_lshl_add_u32 v104, v246, 5, v104
	v_mov_b32_e32 v105, 0
	v_lshl_add_u64 v[100:101], v[100:101], 0, v[104:105]
	s_mov_b64 s[4:5], 0x200000
	s_waitcnt vmcnt(15)
	v_lshlrev_b32_e32 v104, 16, v182
	v_and_b32_e32 v105, 0xffff0000, v182
	v_lshlrev_b32_e32 v106, 16, v183
	v_and_b32_e32 v107, 0xffff0000, v183
	v_lshlrev_b32_e32 v108, 16, v184
	v_and_b32_e32 v109, 0xffff0000, v184
	v_lshlrev_b32_e32 v110, 16, v185
	v_and_b32_e32 v111, 0xffff0000, v185
	global_store_dwordx4 v[100:101], v[104:107], off
	global_store_dwordx4 v[100:101], v[108:111], off offset:16
	v_lshl_add_u64 v[100:101], v[100:101], 0, s[4:5]
	s_waitcnt vmcnt(16)
	v_lshlrev_b32_e32 v104, 16, v186
	v_and_b32_e32 v105, 0xffff0000, v186
	v_lshlrev_b32_e32 v106, 16, v187
	v_and_b32_e32 v107, 0xffff0000, v187
	v_lshlrev_b32_e32 v108, 16, v188
	v_and_b32_e32 v109, 0xffff0000, v188
	v_lshlrev_b32_e32 v110, 16, v189
	v_and_b32_e32 v111, 0xffff0000, v189
	global_store_dwordx4 v[100:101], v[104:107], off
	global_store_dwordx4 v[100:101], v[108:111], off offset:16
	v_lshl_add_u64 v[100:101], v[100:101], 0, s[4:5]
	s_waitcnt vmcnt(17)
	v_lshlrev_b32_e32 v104, 16, v190
	v_and_b32_e32 v105, 0xffff0000, v190
	v_lshlrev_b32_e32 v106, 16, v191
	v_and_b32_e32 v107, 0xffff0000, v191
	v_lshlrev_b32_e32 v108, 16, v192
	v_and_b32_e32 v109, 0xffff0000, v192
	v_lshlrev_b32_e32 v110, 16, v193
	v_and_b32_e32 v111, 0xffff0000, v193
	global_store_dwordx4 v[100:101], v[104:107], off
	global_store_dwordx4 v[100:101], v[108:111], off offset:16
	v_lshl_add_u64 v[100:101], v[100:101], 0, s[4:5]
	s_waitcnt vmcnt(18)
	v_lshlrev_b32_e32 v104, 16, v194
	v_and_b32_e32 v105, 0xffff0000, v194
	v_lshlrev_b32_e32 v106, 16, v195
	v_and_b32_e32 v107, 0xffff0000, v195
	v_lshlrev_b32_e32 v108, 16, v196
	v_and_b32_e32 v109, 0xffff0000, v196
	v_lshlrev_b32_e32 v110, 16, v197
	v_and_b32_e32 v111, 0xffff0000, v197
	global_store_dwordx4 v[100:101], v[104:107], off
	global_store_dwordx4 v[100:101], v[108:111], off offset:16
	v_lshl_add_u64 v[100:101], v[100:101], 0, s[4:5]
	s_waitcnt vmcnt(19)
	v_lshlrev_b32_e32 v104, 16, v198
	v_and_b32_e32 v105, 0xffff0000, v198
	v_lshlrev_b32_e32 v106, 16, v199
	v_and_b32_e32 v107, 0xffff0000, v199
	v_lshlrev_b32_e32 v108, 16, v200
	v_and_b32_e32 v109, 0xffff0000, v200
	v_lshlrev_b32_e32 v110, 16, v201
	v_and_b32_e32 v111, 0xffff0000, v201
	global_store_dwordx4 v[100:101], v[104:107], off
	global_store_dwordx4 v[100:101], v[108:111], off offset:16
	v_lshl_add_u64 v[100:101], v[100:101], 0, s[4:5]
	s_waitcnt vmcnt(20)
	v_lshlrev_b32_e32 v104, 16, v202
	v_and_b32_e32 v105, 0xffff0000, v202
	v_lshlrev_b32_e32 v106, 16, v203
	v_and_b32_e32 v107, 0xffff0000, v203
	v_lshlrev_b32_e32 v108, 16, v204
	v_and_b32_e32 v109, 0xffff0000, v204
	v_lshlrev_b32_e32 v110, 16, v205
	v_and_b32_e32 v111, 0xffff0000, v205
	global_store_dwordx4 v[100:101], v[104:107], off
	global_store_dwordx4 v[100:101], v[108:111], off offset:16
	v_lshl_add_u64 v[100:101], v[100:101], 0, s[4:5]
	s_waitcnt vmcnt(21)
	v_lshlrev_b32_e32 v104, 16, v206
	v_and_b32_e32 v105, 0xffff0000, v206
	v_lshlrev_b32_e32 v106, 16, v207
	v_and_b32_e32 v107, 0xffff0000, v207
	v_lshlrev_b32_e32 v108, 16, v208
	v_and_b32_e32 v109, 0xffff0000, v208
	v_lshlrev_b32_e32 v110, 16, v209
	v_and_b32_e32 v111, 0xffff0000, v209
	global_store_dwordx4 v[100:101], v[104:107], off
	global_store_dwordx4 v[100:101], v[108:111], off offset:16
	v_lshl_add_u64 v[100:101], v[100:101], 0, s[4:5]
	s_waitcnt vmcnt(22)
	v_lshlrev_b32_e32 v104, 16, v210
	v_and_b32_e32 v105, 0xffff0000, v210
	v_lshlrev_b32_e32 v106, 16, v211
	v_and_b32_e32 v107, 0xffff0000, v211
	v_lshlrev_b32_e32 v108, 16, v212
	v_and_b32_e32 v109, 0xffff0000, v212
	v_lshlrev_b32_e32 v110, 16, v213
	v_and_b32_e32 v111, 0xffff0000, v213
	global_store_dwordx4 v[100:101], v[104:107], off
	global_store_dwordx4 v[100:101], v[108:111], off offset:16
	v_lshl_add_u64 v[100:101], v[100:101], 0, s[4:5]
	s_waitcnt vmcnt(23)
	v_lshlrev_b32_e32 v104, 16, v214
	v_and_b32_e32 v105, 0xffff0000, v214
	v_lshlrev_b32_e32 v106, 16, v215
	v_and_b32_e32 v107, 0xffff0000, v215
	v_lshlrev_b32_e32 v108, 16, v216
	v_and_b32_e32 v109, 0xffff0000, v216
	v_lshlrev_b32_e32 v110, 16, v217
	v_and_b32_e32 v111, 0xffff0000, v217
	global_store_dwordx4 v[100:101], v[104:107], off
	global_store_dwordx4 v[100:101], v[108:111], off offset:16
	v_lshl_add_u64 v[100:101], v[100:101], 0, s[4:5]
	s_waitcnt vmcnt(24)
	v_lshlrev_b32_e32 v104, 16, v218
	v_and_b32_e32 v105, 0xffff0000, v218
	v_lshlrev_b32_e32 v106, 16, v219
	v_and_b32_e32 v107, 0xffff0000, v219
	v_lshlrev_b32_e32 v108, 16, v220
	v_and_b32_e32 v109, 0xffff0000, v220
	v_lshlrev_b32_e32 v110, 16, v221
	v_and_b32_e32 v111, 0xffff0000, v221
	global_store_dwordx4 v[100:101], v[104:107], off
	global_store_dwordx4 v[100:101], v[108:111], off offset:16
	v_lshl_add_u64 v[100:101], v[100:101], 0, s[4:5]
	s_waitcnt vmcnt(25)
	v_lshlrev_b32_e32 v104, 16, v222
	v_and_b32_e32 v105, 0xffff0000, v222
	v_lshlrev_b32_e32 v106, 16, v223
	v_and_b32_e32 v107, 0xffff0000, v223
	v_lshlrev_b32_e32 v108, 16, v224
	v_and_b32_e32 v109, 0xffff0000, v224
	v_lshlrev_b32_e32 v110, 16, v225
	v_and_b32_e32 v111, 0xffff0000, v225
	global_store_dwordx4 v[100:101], v[104:107], off
	global_store_dwordx4 v[100:101], v[108:111], off offset:16
	v_lshl_add_u64 v[100:101], v[100:101], 0, s[4:5]
	s_waitcnt vmcnt(26)
	v_lshlrev_b32_e32 v104, 16, v226
	v_and_b32_e32 v105, 0xffff0000, v226
	v_lshlrev_b32_e32 v106, 16, v227
	v_and_b32_e32 v107, 0xffff0000, v227
	v_lshlrev_b32_e32 v108, 16, v228
	v_and_b32_e32 v109, 0xffff0000, v228
	v_lshlrev_b32_e32 v110, 16, v229
	v_and_b32_e32 v111, 0xffff0000, v229
	global_store_dwordx4 v[100:101], v[104:107], off
	global_store_dwordx4 v[100:101], v[108:111], off offset:16
	v_lshl_add_u64 v[100:101], v[100:101], 0, s[4:5]
	s_waitcnt vmcnt(27)
	v_lshlrev_b32_e32 v104, 16, v230
	v_and_b32_e32 v105, 0xffff0000, v230
	v_lshlrev_b32_e32 v106, 16, v231
	v_and_b32_e32 v107, 0xffff0000, v231
	v_lshlrev_b32_e32 v108, 16, v232
	v_and_b32_e32 v109, 0xffff0000, v232
	v_lshlrev_b32_e32 v110, 16, v233
	v_and_b32_e32 v111, 0xffff0000, v233
	global_store_dwordx4 v[100:101], v[104:107], off
	global_store_dwordx4 v[100:101], v[108:111], off offset:16
	v_lshl_add_u64 v[100:101], v[100:101], 0, s[4:5]
	s_waitcnt vmcnt(28)
	v_lshlrev_b32_e32 v104, 16, v234
	v_and_b32_e32 v105, 0xffff0000, v234
	v_lshlrev_b32_e32 v106, 16, v235
	v_and_b32_e32 v107, 0xffff0000, v235
	v_lshlrev_b32_e32 v108, 16, v236
	v_and_b32_e32 v109, 0xffff0000, v236
	v_lshlrev_b32_e32 v110, 16, v237
	v_and_b32_e32 v111, 0xffff0000, v237
	global_store_dwordx4 v[100:101], v[104:107], off
	global_store_dwordx4 v[100:101], v[108:111], off offset:16
	v_lshl_add_u64 v[100:101], v[100:101], 0, s[4:5]
	s_waitcnt vmcnt(29)
	v_lshlrev_b32_e32 v104, 16, v238
	v_and_b32_e32 v105, 0xffff0000, v238
	v_lshlrev_b32_e32 v106, 16, v239
	v_and_b32_e32 v107, 0xffff0000, v239
	v_lshlrev_b32_e32 v108, 16, v240
	v_and_b32_e32 v109, 0xffff0000, v240
	v_lshlrev_b32_e32 v110, 16, v241
	v_and_b32_e32 v111, 0xffff0000, v241
	global_store_dwordx4 v[100:101], v[104:107], off
	global_store_dwordx4 v[100:101], v[108:111], off offset:16
	v_lshl_add_u64 v[100:101], v[100:101], 0, s[4:5]
	s_waitcnt vmcnt(30)
	v_lshlrev_b32_e32 v104, 16, v242
	v_and_b32_e32 v105, 0xffff0000, v242
	v_lshlrev_b32_e32 v106, 16, v243
	v_and_b32_e32 v107, 0xffff0000, v243
	v_lshlrev_b32_e32 v108, 16, v244
	v_and_b32_e32 v109, 0xffff0000, v244
	v_lshlrev_b32_e32 v110, 16, v245
	v_and_b32_e32 v111, 0xffff0000, v245
	global_store_dwordx4 v[100:101], v[104:107], off
	global_store_dwordx4 v[100:101], v[108:111], off offset:16
	s_mov_b64 s[6:7], exec
	s_branch .LBB0_621
	s_mov_b32 s0, 0x200000
	v_cmp_gt_i32_e32 vcc, s0, v11
	s_and_saveexec_b64 s[6:7], vcc
	s_cbranch_execz .LBB0_621
	v_readlane_b32 s0, v252, 47
	s_mov_b64 s[8:9], 0
	s_nop 0
	v_lshl_add_u32 v10, v65, 3, s0
	s_branch .LBB0_602
